# attention B tile loop body rewritten: K and bias fragments requested up front, in-place scores, exp groups between the PV MFMAs
# speedup vs baseline: 1.0077x; 1.0035x over previous
.LBB0_397:
	s_add_i32 s43, s38, -3
	s_cmp_lt_u32 s43, s36
	s_cselect_b64 s[12:13], -1, 0
	s_cmp_gt_i32 s43, s35
	s_cselect_b64 s[44:45], -1, 0
	s_or_b64 s[12:13], s[12:13], s[44:45]
	s_and_b64 vcc, exec, s[12:13]
	s_cbranch_vccnz .LBB0_401
	s_and_b32 s12, s37, 0xc000
	s_add_i32 s12, s12, 0
	v_add_u32_e32 v125, s12, v174
	v_add_u32_e32 v126, v125, v173
	v_add_u32_e32 v127, v125, v177
	v_add_u32_e32 v128, v125, v179
	v_add_u32_e32 v129, v125, v180
	ds_read_b128 v[136:139], v126
	ds_read_b128 v[140:143], v126 offset:4096
	ds_read_b128 v[144:147], v127
	ds_read_b128 v[148:151], v127 offset:4096
	ds_read_b128 v[152:155], v128
	ds_read_b128 v[156:159], v128 offset:4096
	ds_read_b128 v[160:163], v129
	ds_read_b128 v[244:247], v129 offset:4096
	v_and_b32_e32 v130, -16, v118
	v_add_u32_e32 v130, v117, v130
	s_waitcnt lgkmcnt(6)
	v_mfma_f32_32x32x16_bf16 v[32:47], v[136:139], v[64:67], 0
	v_mfma_f32_32x32x16_bf16 v[48:63], v[140:143], v[64:67], 0
	ds_read_b128 v[184:187], v130
	ds_read_b128 v[188:191], v130 offset:32
	ds_read_b128 v[192:195], v130 offset:64
	ds_read_b128 v[200:203], v130 offset:96
	ds_read_b128 v[204:207], v130 offset:128
	ds_read_b128 v[208:211], v130 offset:160
	ds_read_b128 v[248:251], v130 offset:192
	ds_read_b128 v[252:255], v130 offset:224
	s_waitcnt lgkmcnt(12)
	v_mfma_f32_32x32x16_bf16 v[32:47], v[144:147], v[68:71], v[32:47]
	v_mfma_f32_32x32x16_bf16 v[48:63], v[148:151], v[68:71], v[48:63]
	s_waitcnt lgkmcnt(10)
	v_mfma_f32_32x32x16_bf16 v[32:47], v[152:155], v[72:75], v[32:47]
	v_mfma_f32_32x32x16_bf16 v[48:63], v[156:159], v[72:75], v[48:63]
	s_waitcnt lgkmcnt(8)
	v_mfma_f32_32x32x16_bf16 v[32:47], v[160:163], v[76:79], v[32:47]
	v_mfma_f32_32x32x16_bf16 v[48:63], v[244:247], v[76:79], v[48:63]
	v_add_u32_e32 v129, s12, v106
	v_add3_u32 v129, v129, v175, v176
	v_add_u32_e32 v130, v129, v109
	v_add_u32_e32 v129, v129, v107
	s_waitcnt lgkmcnt(0)
	ds_read_b64_tr_b16 v[136:137], v129 offset:8192
	ds_read_b64_tr_b16 v[138:139], v129 offset:9216
	ds_read_b64_tr_b16 v[140:141], v130 offset:8192
	ds_read_b64_tr_b16 v[142:143], v130 offset:9216
	ds_read_b64_tr_b16 v[144:145], v129 offset:10240
	ds_read_b64_tr_b16 v[146:147], v129 offset:11264
	ds_read_b64_tr_b16 v[148:149], v130 offset:10240
	ds_read_b64_tr_b16 v[150:151], v130 offset:11264
	ds_read_b64_tr_b16 v[152:153], v129 offset:12288
	ds_read_b64_tr_b16 v[154:155], v129 offset:13312
	ds_read_b64_tr_b16 v[156:157], v130 offset:12288
	ds_read_b64_tr_b16 v[158:159], v130 offset:13312
	ds_read_b64_tr_b16 v[160:161], v129 offset:14336
	ds_read_b64_tr_b16 v[162:163], v129 offset:15360
	ds_read_b64_tr_b16 v[244:245], v130 offset:14336
	v_fmamk_f32 v32, v32, 0x3e38aa3b, v184
	v_fmamk_f32 v33, v33, 0x3e38aa3b, v185
	v_fmamk_f32 v34, v34, 0x3e38aa3b, v186
	v_fmamk_f32 v35, v35, 0x3e38aa3b, v187
	v_fmamk_f32 v36, v36, 0x3e38aa3b, v188
	v_fmamk_f32 v37, v37, 0x3e38aa3b, v189
	v_fmamk_f32 v38, v38, 0x3e38aa3b, v190
	v_fmamk_f32 v39, v39, 0x3e38aa3b, v191
	v_fmamk_f32 v40, v40, 0x3e38aa3b, v192
	v_fmamk_f32 v41, v41, 0x3e38aa3b, v193
	v_fmamk_f32 v42, v42, 0x3e38aa3b, v194
	v_fmamk_f32 v43, v43, 0x3e38aa3b, v195
	v_fmamk_f32 v44, v44, 0x3e38aa3b, v200
	v_fmamk_f32 v45, v45, 0x3e38aa3b, v201
	v_fmamk_f32 v46, v46, 0x3e38aa3b, v202
	v_fmamk_f32 v47, v47, 0x3e38aa3b, v203
	v_fmamk_f32 v48, v48, 0x3e38aa3b, v204
	v_fmamk_f32 v49, v49, 0x3e38aa3b, v205
	v_fmamk_f32 v50, v50, 0x3e38aa3b, v206
	v_fmamk_f32 v51, v51, 0x3e38aa3b, v207
	v_fmamk_f32 v52, v52, 0x3e38aa3b, v208
	v_fmamk_f32 v53, v53, 0x3e38aa3b, v209
	v_fmamk_f32 v54, v54, 0x3e38aa3b, v210
	v_fmamk_f32 v55, v55, 0x3e38aa3b, v211
	v_fmamk_f32 v56, v56, 0x3e38aa3b, v248
	v_fmamk_f32 v57, v57, 0x3e38aa3b, v249
	v_fmamk_f32 v58, v58, 0x3e38aa3b, v250
	v_fmamk_f32 v59, v59, 0x3e38aa3b, v251
	v_fmamk_f32 v60, v60, 0x3e38aa3b, v252
	v_fmamk_f32 v61, v61, 0x3e38aa3b, v253
	v_fmamk_f32 v62, v62, 0x3e38aa3b, v254
	v_fmamk_f32 v63, v63, 0x3e38aa3b, v255
	v_max3_f32 v125, v32, v33, v34
	v_max3_f32 v126, v35, v36, v37
	v_max3_f32 v127, v38, v39, v40
	v_max3_f32 v128, v41, v42, v43
	v_max3_f32 v125, v125, v44, v45
	v_max3_f32 v126, v126, v46, v47
	v_max3_f32 v127, v127, v48, v49
	v_max3_f32 v128, v128, v50, v51
	v_max3_f32 v125, v125, v52, v53
	v_max3_f32 v126, v126, v54, v55
	v_max3_f32 v127, v127, v56, v57
	v_max3_f32 v128, v128, v58, v59
	v_max3_f32 v125, v125, v60, v61
	v_max3_f32 v126, v126, v62, v63
	v_max3_f32 v125, v125, v126, v127
	v_max_f32_e32 v125, v125, v128
	v_mov_b32_e32 v126, v125
	v_mov_b32_e32 v127, v125
	s_nop 1
	v_permlane32_swap_b32_e32 v126, v127
	v_max_f32_e32 v125, v126, v127
	v_add_f32_e32 v126, 0x41000000, v119
	v_cmp_gt_f32_e32 vcc, v125, v126
	s_cbranch_vccz .Lb_pv
	v_max_f32_e32 v125, v125, v125
	v_max_f32_e32 v127, v119, v119
	v_max_f32_e32 v127, v127, v125
	v_sub_f32_e32 v126, v119, v127
	v_exp_f32_e32 v126, v126
	v_mov_b32_e32 v119, v127
	v_pk_mul_f32 v[0:1], v[0:1], v[126:127] op_sel_hi:[1,0]
	v_pk_mul_f32 v[2:3], v[2:3], v[126:127] op_sel_hi:[1,0]
	v_pk_mul_f32 v[4:5], v[4:5], v[126:127] op_sel_hi:[1,0]
	v_pk_mul_f32 v[6:7], v[6:7], v[126:127] op_sel_hi:[1,0]
	v_pk_mul_f32 v[8:9], v[8:9], v[126:127] op_sel_hi:[1,0]
	v_pk_mul_f32 v[10:11], v[10:11], v[126:127] op_sel_hi:[1,0]
	v_pk_mul_f32 v[12:13], v[12:13], v[126:127] op_sel_hi:[1,0]
	v_pk_mul_f32 v[14:15], v[14:15], v[126:127] op_sel_hi:[1,0]
	v_pk_mul_f32 v[16:17], v[16:17], v[126:127] op_sel_hi:[1,0]
	v_pk_mul_f32 v[18:19], v[18:19], v[126:127] op_sel_hi:[1,0]
	v_pk_mul_f32 v[20:21], v[20:21], v[126:127] op_sel_hi:[1,0]
	v_pk_mul_f32 v[22:23], v[22:23], v[126:127] op_sel_hi:[1,0]
	v_pk_mul_f32 v[24:25], v[24:25], v[126:127] op_sel_hi:[1,0]
	v_pk_mul_f32 v[26:27], v[26:27], v[126:127] op_sel_hi:[1,0]
	v_pk_mul_f32 v[28:29], v[28:29], v[126:127] op_sel_hi:[1,0]
	v_pk_mul_f32 v[30:31], v[30:31], v[126:127] op_sel_hi:[1,0]
	v_mul_f32_e32 v101, v101, v126
.Lb_pv:
	v_sub_f32_e32 v32, v32, v119
	v_exp_f32_e32 v32, v32
	v_sub_f32_e32 v33, v33, v119
	v_exp_f32_e32 v33, v33
	v_sub_f32_e32 v34, v34, v119
	v_exp_f32_e32 v34, v34
	v_sub_f32_e32 v35, v35, v119
	v_exp_f32_e32 v35, v35
	v_sub_f32_e32 v36, v36, v119
	v_exp_f32_e32 v36, v36
	v_sub_f32_e32 v37, v37, v119
	v_exp_f32_e32 v37, v37
	v_sub_f32_e32 v38, v38, v119
	v_exp_f32_e32 v38, v38
	v_sub_f32_e32 v39, v39, v119
	v_exp_f32_e32 v39, v39
	v_add_f32_e32 v125, v32, v33
	v_add_f32_e32 v126, v34, v35
	v_cvt_pk_bf16_f32 v32, v32, v33
	v_cvt_pk_bf16_f32 v33, v34, v35
	v_cvt_pk_bf16_f32 v34, v36, v37
	v_cvt_pk_bf16_f32 v35, v38, v39
	v_add_f32_e32 v127, v36, v37
	v_add_f32_e32 v125, v125, v38
	v_add_f32_e32 v126, v126, v39
	s_waitcnt lgkmcnt(13)
	v_mfma_f32_32x32x16_bf16 v[16:31], v[136:139], v[32:35], v[16:31]
	ds_read_b64_tr_b16 v[246:247], v130 offset:15360
	v_sub_f32_e32 v40, v40, v119
	v_exp_f32_e32 v40, v40
	v_sub_f32_e32 v41, v41, v119
	v_exp_f32_e32 v41, v41
	v_sub_f32_e32 v42, v42, v119
	v_exp_f32_e32 v42, v42
	v_sub_f32_e32 v43, v43, v119
	v_exp_f32_e32 v43, v43
	s_waitcnt lgkmcnt(12)
	v_mfma_f32_32x32x16_bf16 v[0:15], v[140:143], v[32:35], v[0:15]
	v_sub_f32_e32 v44, v44, v119
	v_exp_f32_e32 v44, v44
	v_sub_f32_e32 v45, v45, v119
	v_exp_f32_e32 v45, v45
	v_sub_f32_e32 v46, v46, v119
	v_exp_f32_e32 v46, v46
	v_sub_f32_e32 v47, v47, v119
	v_exp_f32_e32 v47, v47
	v_add_f32_e32 v125, v125, v40
	v_add_f32_e32 v126, v126, v41
	v_add_f32_e32 v127, v127, v42
	v_add_f32_e32 v125, v125, v43
	v_cvt_pk_bf16_f32 v40, v40, v41
	v_cvt_pk_bf16_f32 v41, v42, v43
	v_cvt_pk_bf16_f32 v42, v44, v45
	v_cvt_pk_bf16_f32 v43, v46, v47
	v_add_f32_e32 v126, v126, v44
	v_add_f32_e32 v127, v127, v45
	v_add_f32_e32 v125, v125, v46
	v_add_f32_e32 v126, v126, v47
	s_waitcnt lgkmcnt(10)
	v_mfma_f32_32x32x16_bf16 v[16:31], v[144:147], v[40:43], v[16:31]
	v_sub_f32_e32 v48, v48, v119
	v_exp_f32_e32 v48, v48
	v_sub_f32_e32 v49, v49, v119
	v_exp_f32_e32 v49, v49
	v_sub_f32_e32 v50, v50, v119
	v_exp_f32_e32 v50, v50
	v_sub_f32_e32 v51, v51, v119
	v_exp_f32_e32 v51, v51
	s_waitcnt lgkmcnt(8)
	v_mfma_f32_32x32x16_bf16 v[0:15], v[148:151], v[40:43], v[0:15]
	v_sub_f32_e32 v52, v52, v119
	v_exp_f32_e32 v52, v52
	v_sub_f32_e32 v53, v53, v119
	v_exp_f32_e32 v53, v53
	v_sub_f32_e32 v54, v54, v119
	v_exp_f32_e32 v54, v54
	v_sub_f32_e32 v55, v55, v119
	v_exp_f32_e32 v55, v55
	v_add_f32_e32 v125, v125, v48
	v_add_f32_e32 v126, v126, v49
	v_add_f32_e32 v127, v127, v50
	v_add_f32_e32 v125, v125, v51
	v_cvt_pk_bf16_f32 v48, v48, v49
	v_cvt_pk_bf16_f32 v49, v50, v51
	v_cvt_pk_bf16_f32 v50, v52, v53
	v_cvt_pk_bf16_f32 v51, v54, v55
	v_add_f32_e32 v126, v126, v52
	v_add_f32_e32 v127, v127, v53
	v_add_f32_e32 v125, v125, v54
	v_add_f32_e32 v126, v126, v55
	s_waitcnt lgkmcnt(6)
	v_mfma_f32_32x32x16_bf16 v[16:31], v[152:155], v[48:51], v[16:31]
	v_sub_f32_e32 v56, v56, v119
	v_exp_f32_e32 v56, v56
	v_sub_f32_e32 v57, v57, v119
	v_exp_f32_e32 v57, v57
	v_sub_f32_e32 v58, v58, v119
	v_exp_f32_e32 v58, v58
	v_sub_f32_e32 v59, v59, v119
	v_exp_f32_e32 v59, v59
	s_waitcnt lgkmcnt(4)
	v_mfma_f32_32x32x16_bf16 v[0:15], v[156:159], v[48:51], v[0:15]
	v_sub_f32_e32 v60, v60, v119
	v_exp_f32_e32 v60, v60
	v_sub_f32_e32 v61, v61, v119
	v_exp_f32_e32 v61, v61
	v_sub_f32_e32 v62, v62, v119
	v_exp_f32_e32 v62, v62
	v_sub_f32_e32 v63, v63, v119
	v_exp_f32_e32 v63, v63
	v_add_f32_e32 v125, v125, v56
	v_add_f32_e32 v126, v126, v57
	v_add_f32_e32 v127, v127, v58
	v_add_f32_e32 v125, v125, v59
	v_cvt_pk_bf16_f32 v56, v56, v57
	v_cvt_pk_bf16_f32 v57, v58, v59
	v_cvt_pk_bf16_f32 v58, v60, v61
	v_cvt_pk_bf16_f32 v59, v62, v63
	v_add_f32_e32 v126, v126, v60
	v_add_f32_e32 v127, v127, v61
	v_add_f32_e32 v125, v125, v62
	v_add_f32_e32 v126, v126, v63
	s_waitcnt lgkmcnt(2)
	v_mfma_f32_32x32x16_bf16 v[16:31], v[160:163], v[56:59], v[16:31]
	s_waitcnt lgkmcnt(0)
	v_mfma_f32_32x32x16_bf16 v[0:15], v[244:247], v[56:59], v[0:15]
	v_add_f32_e32 v125, v125, v126
	v_add_f32_e32 v101, v101, v127
	v_add_f32_e32 v101, v101, v125
